# attention C main loop hand-rescheduled: exp/cvt VALU interleaved under S(t+1) MFMAs, V fragments prefetched 4 MFMAs ahead, row sums under last PV MFMAs
# speedup vs baseline: 1.0064x; 1.0043x over previous
.LBB0_742:
	ds_read_b128 v[96:99], v240 offset:17408
	ds_read_b128 v[144:147], v240 offset:26112
	ds_read_b128 v[148:151], v240 offset:17440
	ds_read_b128 v[152:155], v240 offset:26144
	ds_read_b128 v[156:159], v240 offset:17472
	ds_read_b128 v[228:231], v240 offset:26176
	global_load_dwordx4 v[184:187], v247, s[100:101]
	global_load_dwordx4 v[188:191], v252, s[100:101]
	s_waitcnt lgkmcnt(5)
	v_mfma_f32_32x32x16_bf16 v[112:127], v[96:99], v[160:163], 0
	v_exp_f32_e32 v80, v80
	v_exp_f32_e32 v81, v81
	s_waitcnt lgkmcnt(4)
	v_mfma_f32_32x32x16_bf16 v[96:111], v[144:147], v[160:163], 0
	ds_read_b128 v[144:147], v240 offset:17504
	v_exp_f32_e32 v82, v82
	v_exp_f32_e32 v83, v83
	s_waitcnt lgkmcnt(4)
	v_mfma_f32_32x32x16_bf16 v[112:127], v[148:151], v[164:167], v[112:127]
	ds_read_b128 v[148:151], v240 offset:26208
	v_exp_f32_e32 v84, v84
	v_exp_f32_e32 v85, v85
	s_waitcnt lgkmcnt(4)
	v_mfma_f32_32x32x16_bf16 v[96:111], v[152:155], v[164:167], v[96:111]
	v_exp_f32_e32 v86, v86
	v_exp_f32_e32 v87, v87
	v_cvt_pk_bf16_f32 v128, v80, v81
	v_cvt_pk_bf16_f32 v129, v82, v83
	s_waitcnt lgkmcnt(3)
	v_mfma_f32_32x32x16_bf16 v[112:127], v[156:159], v[168:171], v[112:127]
	ds_read_b64_tr_b16 v[152:153], v207 offset:34816
	ds_read_b64_tr_b16 v[154:155], v207 offset:37376
	v_exp_f32_e32 v88, v88
	v_exp_f32_e32 v89, v89
	v_cvt_pk_bf16_f32 v130, v84, v85
	v_cvt_pk_bf16_f32 v131, v86, v87
	s_waitcnt lgkmcnt(4)
	v_mfma_f32_32x32x16_bf16 v[96:111], v[228:231], v[168:171], v[96:111]
	ds_read_b64_tr_b16 v[156:157], v207 offset:34880
	ds_read_b64_tr_b16 v[158:159], v207 offset:37440
	v_exp_f32_e32 v90, v90
	v_exp_f32_e32 v91, v91
	s_waitcnt lgkmcnt(5)
	v_mfma_f32_32x32x16_bf16 v[112:127], v[144:147], v[172:175], v[112:127]
	ds_read_b64_tr_b16 v[228:229], v207 offset:34944
	ds_read_b64_tr_b16 v[230:231], v207 offset:37504
	v_exp_f32_e32 v92, v92
	v_exp_f32_e32 v93, v93
	s_waitcnt lgkmcnt(6)
	v_mfma_f32_32x32x16_bf16 v[96:111], v[148:151], v[172:175], v[96:111]
	ds_read_b64_tr_b16 v[144:145], v207 offset:35008
	ds_read_b64_tr_b16 v[146:147], v207 offset:37568
	v_exp_f32_e32 v94, v94
	v_exp_f32_e32 v95, v95
	v_cvt_pk_bf16_f32 v132, v88, v89
	v_cvt_pk_bf16_f32 v133, v90, v91
	s_waitcnt lgkmcnt(6)
	v_mfma_f32_32x32x16_bf16 v[48:63], v[152:155], v[128:131], v[48:63]
	ds_read_b64_tr_b16 v[148:149], v207 offset:39936
	ds_read_b64_tr_b16 v[150:151], v207 offset:42496
	v_cvt_pk_bf16_f32 v134, v92, v93
	v_cvt_pk_bf16_f32 v135, v94, v95
	v_exp_f32_e32 v64, v64
	v_exp_f32_e32 v65, v65
	s_waitcnt lgkmcnt(6)
	v_mfma_f32_32x32x16_bf16 v[32:47], v[156:159], v[128:131], v[32:47]
	ds_read_b64_tr_b16 v[152:153], v207 offset:40000
	ds_read_b64_tr_b16 v[154:155], v207 offset:42560
	v_exp_f32_e32 v66, v66
	v_exp_f32_e32 v67, v67
	s_waitcnt lgkmcnt(6)
	v_mfma_f32_32x32x16_bf16 v[16:31], v[228:231], v[128:131], v[16:31]
	ds_read_b64_tr_b16 v[156:157], v207 offset:40064
	ds_read_b64_tr_b16 v[158:159], v207 offset:42624
	v_exp_f32_e32 v68, v68
	v_exp_f32_e32 v69, v69
	s_waitcnt lgkmcnt(6)
	v_mfma_f32_32x32x16_bf16 v[0:15], v[144:147], v[128:131], v[0:15]
	ds_read_b64_tr_b16 v[228:229], v207 offset:40128
	ds_read_b64_tr_b16 v[230:231], v207 offset:42688
	v_exp_f32_e32 v70, v70
	v_exp_f32_e32 v71, v71
	s_waitcnt lgkmcnt(6)
	v_mfma_f32_32x32x16_bf16 v[48:63], v[148:151], v[132:135], v[48:63]
	ds_read_b64_tr_b16 v[144:145], v207 offset:45056
	ds_read_b64_tr_b16 v[146:147], v207 offset:47616
	v_cvt_pk_bf16_f32 v136, v64, v65
	v_cvt_pk_bf16_f32 v137, v66, v67
	v_cvt_pk_bf16_f32 v138, v68, v69
	v_cvt_pk_bf16_f32 v139, v70, v71
	v_exp_f32_e32 v72, v72
	s_waitcnt lgkmcnt(6)
	v_mfma_f32_32x32x16_bf16 v[32:47], v[152:155], v[132:135], v[32:47]
	ds_read_b64_tr_b16 v[148:149], v207 offset:45120
	ds_read_b64_tr_b16 v[150:151], v207 offset:47680
	v_exp_f32_e32 v73, v73
	v_exp_f32_e32 v74, v74
	s_waitcnt lgkmcnt(6)
	v_mfma_f32_32x32x16_bf16 v[16:31], v[156:159], v[132:135], v[16:31]
	ds_read_b64_tr_b16 v[152:153], v207 offset:45184
	ds_read_b64_tr_b16 v[154:155], v207 offset:47744
	v_exp_f32_e32 v75, v75
	v_exp_f32_e32 v76, v76
	s_waitcnt lgkmcnt(6)
	v_mfma_f32_32x32x16_bf16 v[0:15], v[228:231], v[132:135], v[0:15]
	ds_read_b64_tr_b16 v[156:157], v207 offset:45248
	ds_read_b64_tr_b16 v[158:159], v207 offset:47808
	v_exp_f32_e32 v77, v77
	v_exp_f32_e32 v78, v78
	s_waitcnt lgkmcnt(6)
	v_mfma_f32_32x32x16_bf16 v[48:63], v[144:147], v[136:139], v[48:63]
	ds_read_b64_tr_b16 v[228:229], v207 offset:50176
	ds_read_b64_tr_b16 v[230:231], v207 offset:52736
	v_exp_f32_e32 v79, v79
	v_cvt_pk_bf16_f32 v140, v72, v73
	v_cvt_pk_bf16_f32 v141, v74, v75
	v_cvt_pk_bf16_f32 v142, v76, v77
	s_waitcnt lgkmcnt(6)
	v_mfma_f32_32x32x16_bf16 v[32:47], v[148:151], v[136:139], v[32:47]
	ds_read_b64_tr_b16 v[144:145], v207 offset:50240
	ds_read_b64_tr_b16 v[146:147], v207 offset:52800
	v_cvt_pk_bf16_f32 v143, v78, v79
	v_pk_add_f32 v[80:81], v[80:81], v[82:83]
	v_pk_add_f32 v[84:85], v[84:85], v[86:87]
	v_pk_add_f32 v[88:89], v[88:89], v[90:91]
	v_pk_add_f32 v[92:93], v[92:93], v[94:95]
	s_waitcnt lgkmcnt(6)
	v_mfma_f32_32x32x16_bf16 v[16:31], v[152:155], v[136:139], v[16:31]
	ds_read_b64_tr_b16 v[148:149], v207 offset:50304
	ds_read_b64_tr_b16 v[150:151], v207 offset:52864
	v_pk_add_f32 v[64:65], v[64:65], v[66:67]
	v_pk_add_f32 v[68:69], v[68:69], v[70:71]
	v_pk_add_f32 v[72:73], v[72:73], v[74:75]
	v_pk_add_f32 v[76:77], v[76:77], v[78:79]
	s_waitcnt lgkmcnt(6)
	v_mfma_f32_32x32x16_bf16 v[0:15], v[156:159], v[136:139], v[0:15]
	ds_read_b64_tr_b16 v[152:153], v207 offset:50368
	ds_read_b64_tr_b16 v[154:155], v207 offset:52928
	v_pk_add_f32 v[80:81], v[80:81], v[84:85]
	v_pk_add_f32 v[88:89], v[88:89], v[92:93]
	v_pk_add_f32 v[64:65], v[64:65], v[68:69]
	v_pk_add_f32 v[72:73], v[72:73], v[76:77]
	s_andn2_b64 vcc, exec, s[20:21]
	s_waitcnt lgkmcnt(6)
	v_mfma_f32_32x32x16_bf16 v[48:63], v[228:231], v[140:143], v[48:63]
	v_pk_add_f32 v[80:81], v[80:81], v[88:89]
	v_pk_add_f32 v[64:65], v[64:65], v[72:73]
	s_waitcnt lgkmcnt(4)
	v_mfma_f32_32x32x16_bf16 v[32:47], v[144:147], v[140:143], v[32:47]
	v_pk_add_f32 v[64:65], v[64:65], v[80:81]
	s_waitcnt lgkmcnt(2)
	v_mfma_f32_32x32x16_bf16 v[16:31], v[148:151], v[140:143], v[16:31]
	v_add_f32_e32 v64, v64, v65
	s_waitcnt lgkmcnt(0)
	v_mfma_f32_32x32x16_bf16 v[0:15], v[152:155], v[140:143], v[0:15]
	v_add_f32_e32 v246, v246, v64
	s_cbranch_vccnz .LBB0_746
	s_waitcnt vmcnt(3)
	ds_write_b128 v192, v[176:179]
	s_waitcnt vmcnt(2)
	ds_write_b128 v215, v[180:183]

.LBB0_748:
	s_or_b32 s24, s17, 1
	s_cmp_lt_u32 s24, 31
	s_cselect_b64 s[22:23], -1, 0
	s_cmp_gt_u32 s24, 30
	s_cbranch_scc1 .LBB0_750
	ds_read_b128 v[64:67], v240
	ds_read_b128 v[144:147], v240 offset:8704
	ds_read_b128 v[148:151], v240 offset:32
	ds_read_b128 v[152:155], v240 offset:8736
	ds_read_b128 v[156:159], v240 offset:64
	ds_read_b128 v[228:231], v240 offset:8768
	global_load_dwordx4 v[184:187], v253, s[100:101]
	global_load_dwordx4 v[188:191], v245, s[100:101]
	s_waitcnt lgkmcnt(5)
	v_mfma_f32_32x32x16_bf16 v[80:95], v[64:67], v[160:163], 0
	v_exp_f32_e32 v112, v112
	v_exp_f32_e32 v113, v113
	s_waitcnt lgkmcnt(4)
	v_mfma_f32_32x32x16_bf16 v[64:79], v[144:147], v[160:163], 0
	ds_read_b128 v[144:147], v240 offset:96
	v_exp_f32_e32 v114, v114
	v_exp_f32_e32 v115, v115
	s_waitcnt lgkmcnt(4)
	v_mfma_f32_32x32x16_bf16 v[80:95], v[148:151], v[164:167], v[80:95]
	ds_read_b128 v[148:151], v240 offset:8800
	v_exp_f32_e32 v116, v116
	v_exp_f32_e32 v117, v117
	s_waitcnt lgkmcnt(4)
	v_mfma_f32_32x32x16_bf16 v[64:79], v[152:155], v[164:167], v[64:79]
	v_exp_f32_e32 v118, v118
	v_exp_f32_e32 v119, v119
	v_cvt_pk_bf16_f32 v128, v112, v113
	v_cvt_pk_bf16_f32 v129, v114, v115
	s_waitcnt lgkmcnt(3)
	v_mfma_f32_32x32x16_bf16 v[80:95], v[156:159], v[168:171], v[80:95]
	ds_read_b64_tr_b16 v[152:153], v207 offset:55296
	ds_read_b64_tr_b16 v[154:155], v207 offset:57856
	v_exp_f32_e32 v120, v120
	v_exp_f32_e32 v121, v121
	v_cvt_pk_bf16_f32 v130, v116, v117
	v_cvt_pk_bf16_f32 v131, v118, v119
	s_waitcnt lgkmcnt(4)
	v_mfma_f32_32x32x16_bf16 v[64:79], v[228:231], v[168:171], v[64:79]
	ds_read_b64_tr_b16 v[156:157], v207 offset:55360
	ds_read_b64_tr_b16 v[158:159], v207 offset:57920
	v_exp_f32_e32 v122, v122
	v_exp_f32_e32 v123, v123
	s_waitcnt lgkmcnt(5)
	v_mfma_f32_32x32x16_bf16 v[80:95], v[144:147], v[172:175], v[80:95]
	ds_read_b64_tr_b16 v[228:229], v207 offset:55424
	ds_read_b64_tr_b16 v[230:231], v207 offset:57984
	v_exp_f32_e32 v124, v124
	v_exp_f32_e32 v125, v125
	s_waitcnt lgkmcnt(6)
	v_mfma_f32_32x32x16_bf16 v[64:79], v[148:151], v[172:175], v[64:79]
	ds_read_b64_tr_b16 v[144:145], v207 offset:55488
	ds_read_b64_tr_b16 v[146:147], v207 offset:58048
	v_exp_f32_e32 v126, v126
	v_exp_f32_e32 v127, v127
	v_cvt_pk_bf16_f32 v132, v120, v121
	v_cvt_pk_bf16_f32 v133, v122, v123
	s_branch .LBB0_751
.LBB0_750:
	ds_read_b64_tr_b16 v[152:153], v207 offset:55296
	ds_read_b64_tr_b16 v[154:155], v207 offset:57856
	ds_read_b64_tr_b16 v[156:157], v207 offset:55360
	ds_read_b64_tr_b16 v[158:159], v207 offset:57920
	ds_read_b64_tr_b16 v[228:229], v207 offset:55424
	ds_read_b64_tr_b16 v[230:231], v207 offset:57984
	ds_read_b64_tr_b16 v[144:145], v207 offset:55488
	ds_read_b64_tr_b16 v[146:147], v207 offset:58048
	v_exp_f32_e32 v112, v112
	v_exp_f32_e32 v113, v113
	v_exp_f32_e32 v114, v114
	v_exp_f32_e32 v115, v115
	v_exp_f32_e32 v116, v116
	v_exp_f32_e32 v117, v117
	v_exp_f32_e32 v118, v118
	v_exp_f32_e32 v119, v119
	v_cvt_pk_bf16_f32 v128, v112, v113
	v_cvt_pk_bf16_f32 v129, v114, v115
	v_cvt_pk_bf16_f32 v130, v116, v117
	v_cvt_pk_bf16_f32 v131, v118, v119
	v_exp_f32_e32 v120, v120
	v_exp_f32_e32 v121, v121
	v_exp_f32_e32 v122, v122
	v_exp_f32_e32 v123, v123
	v_exp_f32_e32 v124, v124
	v_exp_f32_e32 v125, v125
	v_exp_f32_e32 v126, v126
	v_exp_f32_e32 v127, v127
	v_cvt_pk_bf16_f32 v132, v120, v121
	v_cvt_pk_bf16_f32 v133, v122, v123
.LBB0_751:
	s_waitcnt lgkmcnt(6)
	v_mfma_f32_32x32x16_bf16 v[48:63], v[152:155], v[128:131], v[48:63]
	ds_read_b64_tr_b16 v[148:149], v207 offset:60416
	ds_read_b64_tr_b16 v[150:151], v207 offset:62976
	v_cvt_pk_bf16_f32 v134, v124, v125
	v_cvt_pk_bf16_f32 v135, v126, v127
	v_exp_f32_e32 v96, v96
	v_exp_f32_e32 v97, v97
	s_waitcnt lgkmcnt(6)
	v_mfma_f32_32x32x16_bf16 v[32:47], v[156:159], v[128:131], v[32:47]
	ds_read_b64_tr_b16 v[152:153], v207 offset:60480
	ds_read_b64_tr_b16 v[154:155], v207 offset:63040
	v_exp_f32_e32 v98, v98
	v_exp_f32_e32 v99, v99
	s_waitcnt lgkmcnt(6)
	v_mfma_f32_32x32x16_bf16 v[16:31], v[228:231], v[128:131], v[16:31]
	ds_read_b64_tr_b16 v[156:157], v207 offset:60544
	ds_read_b64_tr_b16 v[158:159], v207 offset:63104
	v_exp_f32_e32 v100, v100
	v_exp_f32_e32 v101, v101
	s_waitcnt lgkmcnt(6)
	v_mfma_f32_32x32x16_bf16 v[0:15], v[144:147], v[128:131], v[0:15]
	ds_read_b64_tr_b16 v[228:229], v207 offset:60608
	ds_read_b64_tr_b16 v[230:231], v207 offset:63168
	v_exp_f32_e32 v102, v102
	v_exp_f32_e32 v103, v103
	s_waitcnt lgkmcnt(6)
	v_mfma_f32_32x32x16_bf16 v[48:63], v[148:151], v[132:135], v[48:63]
	ds_read_b64_tr_b16 v[144:145], v209 offset:10240
	ds_read_b64_tr_b16 v[146:147], v209 offset:12800
	v_cvt_pk_bf16_f32 v136, v96, v97
	v_cvt_pk_bf16_f32 v137, v98, v99
	v_cvt_pk_bf16_f32 v138, v100, v101
	v_cvt_pk_bf16_f32 v139, v102, v103
	v_exp_f32_e32 v104, v104
	s_waitcnt lgkmcnt(6)
	v_mfma_f32_32x32x16_bf16 v[32:47], v[152:155], v[132:135], v[32:47]
	ds_read_b64_tr_b16 v[148:149], v209 offset:10304
	ds_read_b64_tr_b16 v[150:151], v209 offset:12864
	v_exp_f32_e32 v105, v105
	v_exp_f32_e32 v106, v106
	s_waitcnt lgkmcnt(6)
	v_mfma_f32_32x32x16_bf16 v[16:31], v[156:159], v[132:135], v[16:31]
	ds_read_b64_tr_b16 v[152:153], v209 offset:10368
	ds_read_b64_tr_b16 v[154:155], v209 offset:12928
	v_exp_f32_e32 v107, v107
	v_exp_f32_e32 v108, v108
	s_waitcnt lgkmcnt(6)
	v_mfma_f32_32x32x16_bf16 v[0:15], v[228:231], v[132:135], v[0:15]
	ds_read_b64_tr_b16 v[156:157], v209 offset:10432
	ds_read_b64_tr_b16 v[158:159], v209 offset:12992
	v_exp_f32_e32 v109, v109
	v_exp_f32_e32 v110, v110
	s_waitcnt lgkmcnt(6)
	v_mfma_f32_32x32x16_bf16 v[48:63], v[144:147], v[136:139], v[48:63]
	ds_read_b64_tr_b16 v[228:229], v209 offset:15360
	ds_read_b64_tr_b16 v[230:231], v209 offset:17920
	v_exp_f32_e32 v111, v111
	v_cvt_pk_bf16_f32 v140, v104, v105
	v_cvt_pk_bf16_f32 v141, v106, v107
	v_cvt_pk_bf16_f32 v142, v108, v109
	s_waitcnt lgkmcnt(6)
	v_mfma_f32_32x32x16_bf16 v[32:47], v[148:151], v[136:139], v[32:47]
	ds_read_b64_tr_b16 v[144:145], v209 offset:15424
	ds_read_b64_tr_b16 v[146:147], v209 offset:17984
	v_cvt_pk_bf16_f32 v143, v110, v111
	v_pk_add_f32 v[112:113], v[112:113], v[114:115]
	v_pk_add_f32 v[116:117], v[116:117], v[118:119]
	v_pk_add_f32 v[120:121], v[120:121], v[122:123]
	v_pk_add_f32 v[124:125], v[124:125], v[126:127]
	s_waitcnt lgkmcnt(6)
	v_mfma_f32_32x32x16_bf16 v[16:31], v[152:155], v[136:139], v[16:31]
	ds_read_b64_tr_b16 v[148:149], v209 offset:15488
	ds_read_b64_tr_b16 v[150:151], v209 offset:18048
	v_pk_add_f32 v[96:97], v[96:97], v[98:99]
	v_pk_add_f32 v[100:101], v[100:101], v[102:103]
	v_pk_add_f32 v[104:105], v[104:105], v[106:107]
	v_pk_add_f32 v[108:109], v[108:109], v[110:111]
	s_waitcnt lgkmcnt(6)
	v_mfma_f32_32x32x16_bf16 v[0:15], v[156:159], v[136:139], v[0:15]
	ds_read_b64_tr_b16 v[152:153], v209 offset:15552
	ds_read_b64_tr_b16 v[154:155], v209 offset:18112
	v_pk_add_f32 v[112:113], v[112:113], v[116:117]
	v_pk_add_f32 v[120:121], v[120:121], v[124:125]
	v_pk_add_f32 v[96:97], v[96:97], v[100:101]
	v_pk_add_f32 v[104:105], v[104:105], v[108:109]
	s_andn2_b64 vcc, exec, s[20:21]
	s_waitcnt lgkmcnt(6)
	v_mfma_f32_32x32x16_bf16 v[48:63], v[228:231], v[140:143], v[48:63]
	v_pk_add_f32 v[112:113], v[112:113], v[120:121]
	v_pk_add_f32 v[96:97], v[96:97], v[104:105]
	s_waitcnt lgkmcnt(4)
	v_mfma_f32_32x32x16_bf16 v[32:47], v[144:147], v[140:143], v[32:47]
	v_pk_add_f32 v[96:97], v[96:97], v[112:113]
	s_waitcnt lgkmcnt(2)
	v_mfma_f32_32x32x16_bf16 v[16:31], v[148:151], v[140:143], v[16:31]
	v_add_f32_e32 v96, v96, v97
	s_waitcnt lgkmcnt(0)
	v_mfma_f32_32x32x16_bf16 v[0:15], v[152:155], v[140:143], v[0:15]
	v_add_f32_e32 v246, v246, v96
	s_cbranch_vccnz .LBB0_755
	s_waitcnt vmcnt(1)
	ds_write_b128 v241, v[176:179] offset:17408
	s_waitcnt vmcnt(0)
	ds_write_b128 v242, v[180:183] offset:17408

.LBB0_757:
	s_add_u32 s18, s18, 0x20000
	s_addc_u32 s19, s19, 0
	s_add_i32 s20, s17, 2
	s_cmp_lt_u32 s17, 29
	s_waitcnt lgkmcnt(0)
	s_barrier
	s_cbranch_scc0 .LBB0_759
	s_add_u32 s98, s98, 0x20000
	s_addc_u32 s99, s99, 0
	s_add_u32 s100, s100, 0x20000
	s_addc_u32 s101, s101, 0
	s_mov_b32 s17, s20
	s_branch .LBB0_740
